# chunk rel-pos near tiles: bias table extended in LDS by its clipped tail so the lookup is one address + 16 ds_read2_b32 with immediate offsets (removes ~96 VALU index ops per tile)
# speedup vs baseline: 1.0002x; 1.0002x over previous
.LBB0_217:
	s_or_b64 exec, exec, s[4:5]
	v_mov_b32_e32 v32, 0
	v_mov_b32_e32 v161, 0
	v_lshlrev_b32_e32 v160, 2, v4
	s_sub_i32 s4, s7, s8
	s_add_i32 s4, s4, 12
	s_ashr_i32 s37, s4, 1
	s_cmp_lt_i32 s37, 1
	v_mul_f32_e32 v168, 0x3fb8aa3b, v11
	v_subrev_u32_e32 v6, 0x140, v216
	v_cmp_gt_u32_e32 vcc, 63, v6
	s_and_saveexec_b64 s[4:5], vcc
	v_lshlrev_b32_e32 v6, 2, v216
	v_add_u32_e32 v6, 0x14000, v6
	ds_write_b32 v6, v168
	s_or_b64 exec, exec, s[4:5]
	s_cmp_lg_u32 s32, 0
	s_cbranch_scc1 .Lpf3_wb
	s_waitcnt vmcnt(0)

.LBB0_225:
	s_or_b32 s5, s20, s4
	s_cmp_lt_u32 s5, s40
	s_cselect_b64 s[8:9], -1, 0
	s_cmp_gt_i32 s5, s39
	s_cselect_b64 s[12:13], -1, 0
	s_or_b64 s[8:9], s[8:9], s[12:13]
	s_and_b64 vcc, exec, s[8:9]
	s_cbranch_vccnz .LBB0_224
	s_or_b32 s8, s20, s41
	s_mul_i32 s9, s8, 0x3000
	v_add_u32_e32 v76, s9, v185
	ds_read_b128 v[48:51], v76
	ds_read_b128 v[52:55], v76 offset:512
	ds_read_b128 v[56:59], v76 offset:2048
	ds_read_b128 v[60:63], v76 offset:2560
	ds_read_b128 v[64:67], v76 offset:4096
	ds_read_b128 v[68:71], v76 offset:4608
	ds_read_b128 v[72:75], v76 offset:6144
	ds_read_b128 v[76:79], v76 offset:6656
	s_waitcnt lgkmcnt(7)
	v_mfma_f32_32x32x16_bf16 v[96:111], v[48:51], v[112:115], v[32:47]
	s_waitcnt lgkmcnt(6)
	v_mfma_f32_32x32x16_bf16 v[80:95], v[52:55], v[112:115], v[32:47]
	s_waitcnt lgkmcnt(5)
	v_mfma_f32_32x32x16_bf16 v[96:111], v[56:59], v[116:119], v[96:111]
	s_waitcnt lgkmcnt(4)
	v_mfma_f32_32x32x16_bf16 v[80:95], v[60:63], v[116:119], v[80:95]
	s_waitcnt lgkmcnt(3)
	v_mfma_f32_32x32x16_bf16 v[96:111], v[64:67], v[120:123], v[96:111]
	s_waitcnt lgkmcnt(2)
	v_mfma_f32_32x32x16_bf16 v[80:95], v[68:71], v[120:123], v[80:95]
	s_waitcnt lgkmcnt(1)
	v_mfma_f32_32x32x16_bf16 v[96:111], v[72:75], v[124:127], v[96:111]
	s_waitcnt lgkmcnt(0)
	v_mfma_f32_32x32x16_bf16 v[80:95], v[76:79], v[124:127], v[80:95]
	v_lshl_add_u32 v48, s8, 13, v186
	ds_read_b64_tr_b16 v[156:157], v48 offset:49152
	ds_read_b64_tr_b16 v[158:159], v48 offset:49664
	ds_read_b64_tr_b16 v[152:153], v48 offset:50176
	ds_read_b64_tr_b16 v[154:155], v48 offset:50688
	ds_read_b64_tr_b16 v[148:149], v48 offset:53248
	ds_read_b64_tr_b16 v[150:151], v48 offset:53760
	ds_read_b64_tr_b16 v[144:145], v48 offset:54272
	ds_read_b64_tr_b16 v[146:147], v48 offset:54784
	ds_read_b64_tr_b16 v[140:141], v48 offset:51200
	ds_read_b64_tr_b16 v[142:143], v48 offset:51712
	ds_read_b64_tr_b16 v[128:129], v48 offset:52224
	ds_read_b64_tr_b16 v[130:131], v48 offset:52736
	ds_read_b64_tr_b16 v[136:137], v48 offset:55296
	ds_read_b64_tr_b16 v[138:139], v48 offset:55808
	ds_read_b64_tr_b16 v[132:133], v48 offset:56320
	ds_read_b64_tr_b16 v[134:135], v48 offset:56832
	s_cmp_ge_i32 s5, s18
	s_mov_b64 s[8:9], -1
	s_cbranch_scc0 .LBB0_228
	s_lshl_b32 s5, s5, 6
	v_subrev_u32_e32 v60, s5, v187
	s_add_i32 s5, 0, 0x14000
	v_lshl_add_u32 v188, v60, 2, s5
	ds_read2_b32 v[48:49], v188 offset0:63 offset1:62
	ds_read2_b32 v[50:51], v188 offset0:61 offset1:60
	ds_read2_b32 v[52:53], v188 offset0:55 offset1:54
	ds_read2_b32 v[54:55], v188 offset0:53 offset1:52
	ds_read2_b32 v[56:57], v188 offset0:47 offset1:46
	ds_read2_b32 v[58:59], v188 offset0:45 offset1:44
	ds_read2_b32 v[60:61], v188 offset0:39 offset1:38
	ds_read2_b32 v[62:63], v188 offset0:37 offset1:36
	ds_read2_b32 v[64:65], v188 offset0:31 offset1:30
	ds_read2_b32 v[66:67], v188 offset0:29 offset1:28
	ds_read2_b32 v[68:69], v188 offset0:23 offset1:22
	ds_read2_b32 v[70:71], v188 offset0:21 offset1:20
	ds_read2_b32 v[72:73], v188 offset0:15 offset1:14
	ds_read2_b32 v[74:75], v188 offset0:13 offset1:12
	ds_read2_b32 v[76:77], v188 offset0:7 offset1:6
	ds_read2_b32 v[78:79], v188 offset0:5 offset1:4
	s_waitcnt lgkmcnt(15)
	v_pk_add_f32 v[48:49], v[96:97], v[48:49]
	s_waitcnt lgkmcnt(14)
	v_pk_add_f32 v[50:51], v[98:99], v[50:51]
	s_waitcnt lgkmcnt(13)
	v_pk_add_f32 v[52:53], v[100:101], v[52:53]
	s_waitcnt lgkmcnt(12)
	v_pk_add_f32 v[54:55], v[102:103], v[54:55]
	s_waitcnt lgkmcnt(11)
	v_pk_add_f32 v[56:57], v[104:105], v[56:57]
	s_waitcnt lgkmcnt(10)
	v_pk_add_f32 v[58:59], v[106:107], v[58:59]
	s_waitcnt lgkmcnt(9)
	v_pk_add_f32 v[60:61], v[108:109], v[60:61]
	s_waitcnt lgkmcnt(8)
	v_pk_add_f32 v[62:63], v[110:111], v[62:63]
	s_waitcnt lgkmcnt(7)
	v_pk_add_f32 v[64:65], v[80:81], v[64:65]
	s_waitcnt lgkmcnt(6)
	v_pk_add_f32 v[66:67], v[82:83], v[66:67]
	s_waitcnt lgkmcnt(5)
	v_pk_add_f32 v[68:69], v[84:85], v[68:69]
	s_waitcnt lgkmcnt(4)
	v_pk_add_f32 v[70:71], v[86:87], v[70:71]
	s_waitcnt lgkmcnt(3)
	v_pk_add_f32 v[72:73], v[88:89], v[72:73]
	s_waitcnt lgkmcnt(2)
	v_pk_add_f32 v[74:75], v[90:91], v[74:75]
	s_waitcnt lgkmcnt(1)
	v_pk_add_f32 v[76:77], v[92:93], v[76:77]
	s_waitcnt lgkmcnt(0)
	v_pk_add_f32 v[78:79], v[94:95], v[78:79]
	s_mov_b64 s[8:9], 0
